# mixers: lru final epilogue rewritten with its 32 gate loads issued up front; spatial-gating LN gamma/data loads batched (were 36 serialized load-wait round trips per tile)
# speedup vs baseline: 1.0146x; 1.0146x over previous
.LBB0_463:
	s_ashr_i32 s24, s36, 31
	s_ashr_i32 s29, s37, 31
	s_add_u32 s28, s37, s36
	s_addc_u32 s29, s29, s24
	v_lshl_add_u64 v[38:39], s[28:29], 0, v[66:67]
	v_lshlrev_b64 v[40:41], 13, v[38:39]
	v_lshlrev_b64 v[36:37], 1, v[68:69]
	v_lshl_add_u64 v[40:41], s[0:1], 0, v[40:41]
	v_lshl_add_u64 v[40:41], v[40:41], 0, v[36:37]
	v_add_co_u32_e32 v40, vcc, s77, v40
	v_lshl_add_u64 v[18:19], s[52:53], 0, v[36:37]
	s_nop 0
	v_addc_co_u32_e32 v41, vcc, 0, v41, vcc
	v_lshlrev_b64 v[42:43], 12, v[38:39]
	v_lshl_add_u64 v[42:43], v[18:19], 0, v[42:43]
	s_mov_b64 s[86:87], 0x2000
	s_mov_b64 s[88:89], 0x1a000
	global_load_ushort v160, v[40:41], off
	v_lshl_add_u64 v[40:41], v[40:41], 0, s[86:87]
	global_load_ushort v161, v[40:41], off
	v_lshl_add_u64 v[40:41], v[40:41], 0, s[86:87]
	global_load_ushort v162, v[40:41], off
	v_lshl_add_u64 v[40:41], v[40:41], 0, s[86:87]
	global_load_ushort v163, v[40:41], off
	v_lshl_add_u64 v[40:41], v[40:41], 0, s[88:89]
	global_load_ushort v164, v[40:41], off
	v_lshl_add_u64 v[40:41], v[40:41], 0, s[86:87]
	global_load_ushort v165, v[40:41], off
	v_lshl_add_u64 v[40:41], v[40:41], 0, s[86:87]
	global_load_ushort v166, v[40:41], off
	v_lshl_add_u64 v[40:41], v[40:41], 0, s[86:87]
	global_load_ushort v167, v[40:41], off
	v_lshl_add_u64 v[40:41], v[40:41], 0, s[88:89]
	global_load_ushort v168, v[40:41], off
	v_lshl_add_u64 v[40:41], v[40:41], 0, s[86:87]
	global_load_ushort v169, v[40:41], off
	v_lshl_add_u64 v[40:41], v[40:41], 0, s[86:87]
	global_load_ushort v170, v[40:41], off
	v_lshl_add_u64 v[40:41], v[40:41], 0, s[86:87]
	global_load_ushort v171, v[40:41], off
	v_lshl_add_u64 v[40:41], v[40:41], 0, s[88:89]
	global_load_ushort v172, v[40:41], off
	v_lshl_add_u64 v[40:41], v[40:41], 0, s[86:87]
	global_load_ushort v173, v[40:41], off
	v_lshl_add_u64 v[40:41], v[40:41], 0, s[86:87]
	global_load_ushort v174, v[40:41], off
	v_lshl_add_u64 v[40:41], v[40:41], 0, s[86:87]
	global_load_ushort v175, v[40:41], off
	v_lshl_add_u64 v[40:41], v[40:41], 0, s[88:89]
	global_load_ushort v176, v[40:41], off
	v_lshl_add_u64 v[40:41], v[40:41], 0, s[86:87]
	global_load_ushort v177, v[40:41], off
	v_lshl_add_u64 v[40:41], v[40:41], 0, s[86:87]
	global_load_ushort v178, v[40:41], off
	v_lshl_add_u64 v[40:41], v[40:41], 0, s[86:87]
	global_load_ushort v179, v[40:41], off
	v_lshl_add_u64 v[40:41], v[40:41], 0, s[88:89]
	global_load_ushort v180, v[40:41], off
	v_lshl_add_u64 v[40:41], v[40:41], 0, s[86:87]
	global_load_ushort v181, v[40:41], off
	v_lshl_add_u64 v[40:41], v[40:41], 0, s[86:87]
	global_load_ushort v182, v[40:41], off
	v_lshl_add_u64 v[40:41], v[40:41], 0, s[86:87]
	global_load_ushort v183, v[40:41], off
	v_lshl_add_u64 v[40:41], v[40:41], 0, s[88:89]
	global_load_ushort v184, v[40:41], off
	v_lshl_add_u64 v[40:41], v[40:41], 0, s[86:87]
	global_load_ushort v185, v[40:41], off
	v_lshl_add_u64 v[40:41], v[40:41], 0, s[86:87]
	global_load_ushort v186, v[40:41], off
	v_lshl_add_u64 v[40:41], v[40:41], 0, s[86:87]
	global_load_ushort v187, v[40:41], off
	v_lshl_add_u64 v[40:41], v[40:41], 0, s[88:89]
	global_load_ushort v188, v[40:41], off
	v_lshl_add_u64 v[40:41], v[40:41], 0, s[86:87]
	global_load_ushort v189, v[40:41], off
	v_lshl_add_u64 v[40:41], v[40:41], 0, s[86:87]
	global_load_ushort v190, v[40:41], off
	v_lshl_add_u64 v[40:41], v[40:41], 0, s[86:87]
	global_load_ushort v191, v[40:41], off
	s_mov_b64 s[86:87], 0x1000
	s_mov_b64 s[88:89], 0xd000
	s_waitcnt vmcnt(31)
	v_lshlrev_b32_e32 v16, 16, v160
	v_mul_f32_e32 v40, 0x3d372713, v16
	v_mul_f32_e32 v40, v40, v16
	v_fma_f32 v40, v40, v16, v16
	v_mul_f32_e32 v40, 0x3f4c422a, v40
	v_add_f32_e32 v40, v40, v40
	v_mul_f32_e32 v40, 0xbfb8aa3b, v40
	v_exp_f32_e32 v40, v40
	s_nop 0
	v_add_f32_e32 v40, 1.0, v40
	v_rcp_f32_e32 v40, v40
	s_nop 0
	v_mul_f32_e32 v16, v40, v16
	v_mul_f32_e32 v16, v32, v16
	v_cvt_pk_bf16_f32 v16, v16, v17
	global_store_short v[42:43], v16, off
	v_lshl_add_u64 v[42:43], v[42:43], 0, s[86:87]
	s_waitcnt vmcnt(31)
	v_lshlrev_b32_e32 v16, 16, v161
	v_mul_f32_e32 v40, 0x3d372713, v16
	v_mul_f32_e32 v40, v40, v16
	v_fma_f32 v40, v40, v16, v16
	v_mul_f32_e32 v40, 0x3f4c422a, v40
	v_add_f32_e32 v40, v40, v40
	v_mul_f32_e32 v40, 0xbfb8aa3b, v40
	v_exp_f32_e32 v40, v40
	s_nop 0
	v_add_f32_e32 v40, 1.0, v40
	v_rcp_f32_e32 v40, v40
	s_nop 0
	v_mul_f32_e32 v16, v40, v16
	v_mul_f32_e32 v16, v33, v16
	v_cvt_pk_bf16_f32 v16, v16, v17
	global_store_short v[42:43], v16, off
	v_lshl_add_u64 v[42:43], v[42:43], 0, s[86:87]
	s_waitcnt vmcnt(31)
	v_lshlrev_b32_e32 v16, 16, v162
	v_mul_f32_e32 v40, 0x3d372713, v16
	v_mul_f32_e32 v40, v40, v16
	v_fma_f32 v40, v40, v16, v16
	v_mul_f32_e32 v40, 0x3f4c422a, v40
	v_add_f32_e32 v40, v40, v40
	v_mul_f32_e32 v40, 0xbfb8aa3b, v40
	v_exp_f32_e32 v40, v40
	s_nop 0
	v_add_f32_e32 v40, 1.0, v40
	v_rcp_f32_e32 v40, v40
	s_nop 0
	v_mul_f32_e32 v16, v40, v16
	v_mul_f32_e32 v16, v34, v16
	v_cvt_pk_bf16_f32 v16, v16, v17
	global_store_short v[42:43], v16, off
	v_lshl_add_u64 v[42:43], v[42:43], 0, s[86:87]
	s_waitcnt vmcnt(31)
	v_lshlrev_b32_e32 v16, 16, v163
	v_mul_f32_e32 v40, 0x3d372713, v16
	v_mul_f32_e32 v40, v40, v16
	v_fma_f32 v40, v40, v16, v16
	v_mul_f32_e32 v40, 0x3f4c422a, v40
	v_add_f32_e32 v40, v40, v40
	v_mul_f32_e32 v40, 0xbfb8aa3b, v40
	v_exp_f32_e32 v40, v40
	s_nop 0
	v_add_f32_e32 v40, 1.0, v40
	v_rcp_f32_e32 v40, v40
	s_nop 0
	v_mul_f32_e32 v16, v40, v16
	v_mul_f32_e32 v16, v35, v16
	v_cvt_pk_bf16_f32 v16, v16, v17
	global_store_short v[42:43], v16, off
	v_lshl_add_u64 v[42:43], v[42:43], 0, s[88:89]
	s_waitcnt vmcnt(31)
	v_lshlrev_b32_e32 v16, 16, v164
	v_mul_f32_e32 v40, 0x3d372713, v16
	v_mul_f32_e32 v40, v40, v16
	v_fma_f32 v40, v40, v16, v16
	v_mul_f32_e32 v40, 0x3f4c422a, v40
	v_add_f32_e32 v40, v40, v40
	v_mul_f32_e32 v40, 0xbfb8aa3b, v40
	v_exp_f32_e32 v40, v40
	s_nop 0
	v_add_f32_e32 v40, 1.0, v40
	v_rcp_f32_e32 v40, v40
	s_nop 0
	v_mul_f32_e32 v16, v40, v16
	v_mul_f32_e32 v16, v28, v16
	v_cvt_pk_bf16_f32 v16, v16, v17
	global_store_short v[42:43], v16, off
	v_lshl_add_u64 v[42:43], v[42:43], 0, s[86:87]
	s_waitcnt vmcnt(31)
	v_lshlrev_b32_e32 v16, 16, v165
	v_mul_f32_e32 v40, 0x3d372713, v16
	v_mul_f32_e32 v40, v40, v16
	v_fma_f32 v40, v40, v16, v16
	v_mul_f32_e32 v40, 0x3f4c422a, v40
	v_add_f32_e32 v40, v40, v40
	v_mul_f32_e32 v40, 0xbfb8aa3b, v40
	v_exp_f32_e32 v40, v40
	s_nop 0
	v_add_f32_e32 v40, 1.0, v40
	v_rcp_f32_e32 v40, v40
	s_nop 0
	v_mul_f32_e32 v16, v40, v16
	v_mul_f32_e32 v16, v29, v16
	v_cvt_pk_bf16_f32 v16, v16, v17
	global_store_short v[42:43], v16, off
	v_lshl_add_u64 v[42:43], v[42:43], 0, s[86:87]
	s_waitcnt vmcnt(31)
	v_lshlrev_b32_e32 v16, 16, v166
	v_mul_f32_e32 v40, 0x3d372713, v16
	v_mul_f32_e32 v40, v40, v16
	v_fma_f32 v40, v40, v16, v16
	v_mul_f32_e32 v40, 0x3f4c422a, v40
	v_add_f32_e32 v40, v40, v40
	v_mul_f32_e32 v40, 0xbfb8aa3b, v40
	v_exp_f32_e32 v40, v40
	s_nop 0
	v_add_f32_e32 v40, 1.0, v40
	v_rcp_f32_e32 v40, v40
	s_nop 0
	v_mul_f32_e32 v16, v40, v16
	v_mul_f32_e32 v16, v30, v16
	v_cvt_pk_bf16_f32 v16, v16, v17
	global_store_short v[42:43], v16, off
	v_lshl_add_u64 v[42:43], v[42:43], 0, s[86:87]
	s_waitcnt vmcnt(31)
	v_lshlrev_b32_e32 v16, 16, v167
	v_mul_f32_e32 v40, 0x3d372713, v16
	v_mul_f32_e32 v40, v40, v16
	v_fma_f32 v40, v40, v16, v16
	v_mul_f32_e32 v40, 0x3f4c422a, v40
	v_add_f32_e32 v40, v40, v40
	v_mul_f32_e32 v40, 0xbfb8aa3b, v40
	v_exp_f32_e32 v40, v40
	s_nop 0
	v_add_f32_e32 v40, 1.0, v40
	v_rcp_f32_e32 v40, v40
	s_nop 0
	v_mul_f32_e32 v16, v40, v16
	v_mul_f32_e32 v16, v31, v16
	v_cvt_pk_bf16_f32 v16, v16, v17
	global_store_short v[42:43], v16, off
	v_lshl_add_u64 v[42:43], v[42:43], 0, s[88:89]
	s_waitcnt vmcnt(31)
	v_lshlrev_b32_e32 v16, 16, v168
	v_mul_f32_e32 v40, 0x3d372713, v16
	v_mul_f32_e32 v40, v40, v16
	v_fma_f32 v40, v40, v16, v16
	v_mul_f32_e32 v40, 0x3f4c422a, v40
	v_add_f32_e32 v40, v40, v40
	v_mul_f32_e32 v40, 0xbfb8aa3b, v40
	v_exp_f32_e32 v40, v40
	s_nop 0
	v_add_f32_e32 v40, 1.0, v40
	v_rcp_f32_e32 v40, v40
	s_nop 0
	v_mul_f32_e32 v16, v40, v16
	v_mul_f32_e32 v16, v24, v16
	v_cvt_pk_bf16_f32 v16, v16, v17
	global_store_short v[42:43], v16, off
	v_lshl_add_u64 v[42:43], v[42:43], 0, s[86:87]
	s_waitcnt vmcnt(31)
	v_lshlrev_b32_e32 v16, 16, v169
	v_mul_f32_e32 v40, 0x3d372713, v16
	v_mul_f32_e32 v40, v40, v16
	v_fma_f32 v40, v40, v16, v16
	v_mul_f32_e32 v40, 0x3f4c422a, v40
	v_add_f32_e32 v40, v40, v40
	v_mul_f32_e32 v40, 0xbfb8aa3b, v40
	v_exp_f32_e32 v40, v40
	s_nop 0
	v_add_f32_e32 v40, 1.0, v40
	v_rcp_f32_e32 v40, v40
	s_nop 0
	v_mul_f32_e32 v16, v40, v16
	v_mul_f32_e32 v16, v25, v16
	v_cvt_pk_bf16_f32 v16, v16, v17
	global_store_short v[42:43], v16, off
	v_lshl_add_u64 v[42:43], v[42:43], 0, s[86:87]
	s_waitcnt vmcnt(31)
	v_lshlrev_b32_e32 v16, 16, v170
	v_mul_f32_e32 v40, 0x3d372713, v16
	v_mul_f32_e32 v40, v40, v16
	v_fma_f32 v40, v40, v16, v16
	v_mul_f32_e32 v40, 0x3f4c422a, v40
	v_add_f32_e32 v40, v40, v40
	v_mul_f32_e32 v40, 0xbfb8aa3b, v40
	v_exp_f32_e32 v40, v40
	s_nop 0
	v_add_f32_e32 v40, 1.0, v40
	v_rcp_f32_e32 v40, v40
	s_nop 0
	v_mul_f32_e32 v16, v40, v16
	v_mul_f32_e32 v16, v26, v16
	v_cvt_pk_bf16_f32 v16, v16, v17
	global_store_short v[42:43], v16, off
	v_lshl_add_u64 v[42:43], v[42:43], 0, s[86:87]
	s_waitcnt vmcnt(31)
	v_lshlrev_b32_e32 v16, 16, v171
	v_mul_f32_e32 v40, 0x3d372713, v16
	v_mul_f32_e32 v40, v40, v16
	v_fma_f32 v40, v40, v16, v16
	v_mul_f32_e32 v40, 0x3f4c422a, v40
	v_add_f32_e32 v40, v40, v40
	v_mul_f32_e32 v40, 0xbfb8aa3b, v40
	v_exp_f32_e32 v40, v40
	s_nop 0
	v_add_f32_e32 v40, 1.0, v40
	v_rcp_f32_e32 v40, v40
	s_nop 0
	v_mul_f32_e32 v16, v40, v16
	v_mul_f32_e32 v16, v27, v16
	v_cvt_pk_bf16_f32 v16, v16, v17
	global_store_short v[42:43], v16, off
	v_lshl_add_u64 v[42:43], v[42:43], 0, s[88:89]
	s_waitcnt vmcnt(31)
	v_lshlrev_b32_e32 v16, 16, v172
	v_mul_f32_e32 v40, 0x3d372713, v16
	v_mul_f32_e32 v40, v40, v16
	v_fma_f32 v40, v40, v16, v16
	v_mul_f32_e32 v40, 0x3f4c422a, v40
	v_add_f32_e32 v40, v40, v40
	v_mul_f32_e32 v40, 0xbfb8aa3b, v40
	v_exp_f32_e32 v40, v40
	s_nop 0
	v_add_f32_e32 v40, 1.0, v40
	v_rcp_f32_e32 v40, v40
	s_nop 0
	v_mul_f32_e32 v16, v40, v16
	v_mul_f32_e32 v16, v20, v16
	v_cvt_pk_bf16_f32 v16, v16, v17
	global_store_short v[42:43], v16, off
	v_lshl_add_u64 v[42:43], v[42:43], 0, s[86:87]
	s_waitcnt vmcnt(31)
	v_lshlrev_b32_e32 v16, 16, v173
	v_mul_f32_e32 v40, 0x3d372713, v16
	v_mul_f32_e32 v40, v40, v16
	v_fma_f32 v40, v40, v16, v16
	v_mul_f32_e32 v40, 0x3f4c422a, v40
	v_add_f32_e32 v40, v40, v40
	v_mul_f32_e32 v40, 0xbfb8aa3b, v40
	v_exp_f32_e32 v40, v40
	s_nop 0
	v_add_f32_e32 v40, 1.0, v40
	v_rcp_f32_e32 v40, v40
	s_nop 0
	v_mul_f32_e32 v16, v40, v16
	v_mul_f32_e32 v16, v21, v16
	v_cvt_pk_bf16_f32 v16, v16, v17
	global_store_short v[42:43], v16, off
	v_lshl_add_u64 v[42:43], v[42:43], 0, s[86:87]
	s_waitcnt vmcnt(31)
	v_lshlrev_b32_e32 v16, 16, v174
	v_mul_f32_e32 v40, 0x3d372713, v16
	v_mul_f32_e32 v40, v40, v16
	v_fma_f32 v40, v40, v16, v16
	v_mul_f32_e32 v40, 0x3f4c422a, v40
	v_add_f32_e32 v40, v40, v40
	v_mul_f32_e32 v40, 0xbfb8aa3b, v40
	v_exp_f32_e32 v40, v40
	s_nop 0
	v_add_f32_e32 v40, 1.0, v40
	v_rcp_f32_e32 v40, v40
	s_nop 0
	v_mul_f32_e32 v16, v40, v16
	v_mul_f32_e32 v16, v22, v16
	v_cvt_pk_bf16_f32 v16, v16, v17
	global_store_short v[42:43], v16, off
	v_lshl_add_u64 v[42:43], v[42:43], 0, s[86:87]
	s_waitcnt vmcnt(31)
	v_lshlrev_b32_e32 v16, 16, v175
	v_mul_f32_e32 v40, 0x3d372713, v16
	v_mul_f32_e32 v40, v40, v16
	v_fma_f32 v40, v40, v16, v16
	v_mul_f32_e32 v40, 0x3f4c422a, v40
	v_add_f32_e32 v40, v40, v40
	v_mul_f32_e32 v40, 0xbfb8aa3b, v40
	v_exp_f32_e32 v40, v40
	s_nop 0
	v_add_f32_e32 v40, 1.0, v40
	v_rcp_f32_e32 v40, v40
	s_nop 0
	v_mul_f32_e32 v16, v40, v16
	v_mul_f32_e32 v16, v23, v16
	v_cvt_pk_bf16_f32 v16, v16, v17
	global_store_short v[42:43], v16, off
	v_lshl_add_u64 v[42:43], v[42:43], 0, s[88:89]
	s_waitcnt vmcnt(31)
	v_lshlrev_b32_e32 v16, 16, v176
	v_mul_f32_e32 v40, 0x3d372713, v16
	v_mul_f32_e32 v40, v40, v16
	v_fma_f32 v40, v40, v16, v16
	v_mul_f32_e32 v40, 0x3f4c422a, v40
	v_add_f32_e32 v40, v40, v40
	v_mul_f32_e32 v40, 0xbfb8aa3b, v40
	v_exp_f32_e32 v40, v40
	s_nop 0
	v_add_f32_e32 v40, 1.0, v40
	v_rcp_f32_e32 v40, v40
	s_nop 0
	v_mul_f32_e32 v16, v40, v16
	v_mul_f32_e32 v16, v12, v16
	v_cvt_pk_bf16_f32 v16, v16, v17
	global_store_short v[42:43], v16, off
	v_lshl_add_u64 v[42:43], v[42:43], 0, s[86:87]
	s_waitcnt vmcnt(31)
	v_lshlrev_b32_e32 v16, 16, v177
	v_mul_f32_e32 v40, 0x3d372713, v16
	v_mul_f32_e32 v40, v40, v16
	v_fma_f32 v40, v40, v16, v16
	v_mul_f32_e32 v40, 0x3f4c422a, v40
	v_add_f32_e32 v40, v40, v40
	v_mul_f32_e32 v40, 0xbfb8aa3b, v40
	v_exp_f32_e32 v40, v40
	s_nop 0
	v_add_f32_e32 v40, 1.0, v40
	v_rcp_f32_e32 v40, v40
	s_nop 0
	v_mul_f32_e32 v16, v40, v16
	v_mul_f32_e32 v16, v13, v16
	v_cvt_pk_bf16_f32 v16, v16, v17
	global_store_short v[42:43], v16, off
	v_lshl_add_u64 v[42:43], v[42:43], 0, s[86:87]
	s_waitcnt vmcnt(31)
	v_lshlrev_b32_e32 v16, 16, v178
	v_mul_f32_e32 v40, 0x3d372713, v16
	v_mul_f32_e32 v40, v40, v16
	v_fma_f32 v40, v40, v16, v16
	v_mul_f32_e32 v40, 0x3f4c422a, v40
	v_add_f32_e32 v40, v40, v40
	v_mul_f32_e32 v40, 0xbfb8aa3b, v40
	v_exp_f32_e32 v40, v40
	s_nop 0
	v_add_f32_e32 v40, 1.0, v40
	v_rcp_f32_e32 v40, v40
	s_nop 0
	v_mul_f32_e32 v16, v40, v16
	v_mul_f32_e32 v16, v14, v16
	v_cvt_pk_bf16_f32 v16, v16, v17
	global_store_short v[42:43], v16, off
	v_lshl_add_u64 v[42:43], v[42:43], 0, s[86:87]
	s_waitcnt vmcnt(31)
	v_lshlrev_b32_e32 v16, 16, v179
	v_mul_f32_e32 v40, 0x3d372713, v16
	v_mul_f32_e32 v40, v40, v16
	v_fma_f32 v40, v40, v16, v16
	v_mul_f32_e32 v40, 0x3f4c422a, v40
	v_add_f32_e32 v40, v40, v40
	v_mul_f32_e32 v40, 0xbfb8aa3b, v40
	v_exp_f32_e32 v40, v40
	s_nop 0
	v_add_f32_e32 v40, 1.0, v40
	v_rcp_f32_e32 v40, v40
	s_nop 0
	v_mul_f32_e32 v16, v40, v16
	v_mul_f32_e32 v16, v15, v16
	v_cvt_pk_bf16_f32 v16, v16, v17
	global_store_short v[42:43], v16, off
	v_lshl_add_u64 v[42:43], v[42:43], 0, s[88:89]
	s_waitcnt vmcnt(31)
	v_lshlrev_b32_e32 v16, 16, v180
	v_mul_f32_e32 v40, 0x3d372713, v16
	v_mul_f32_e32 v40, v40, v16
	v_fma_f32 v40, v40, v16, v16
	v_mul_f32_e32 v40, 0x3f4c422a, v40
	v_add_f32_e32 v40, v40, v40
	v_mul_f32_e32 v40, 0xbfb8aa3b, v40
	v_exp_f32_e32 v40, v40
	s_nop 0
	v_add_f32_e32 v40, 1.0, v40
	v_rcp_f32_e32 v40, v40
	s_nop 0
	v_mul_f32_e32 v16, v40, v16
	v_mul_f32_e32 v16, v8, v16
	v_cvt_pk_bf16_f32 v16, v16, v17
	global_store_short v[42:43], v16, off
	v_lshl_add_u64 v[42:43], v[42:43], 0, s[86:87]
	s_waitcnt vmcnt(31)
	v_lshlrev_b32_e32 v16, 16, v181
	v_mul_f32_e32 v40, 0x3d372713, v16
	v_mul_f32_e32 v40, v40, v16
	v_fma_f32 v40, v40, v16, v16
	v_mul_f32_e32 v40, 0x3f4c422a, v40
	v_add_f32_e32 v40, v40, v40
	v_mul_f32_e32 v40, 0xbfb8aa3b, v40
	v_exp_f32_e32 v40, v40
	s_nop 0
	v_add_f32_e32 v40, 1.0, v40
	v_rcp_f32_e32 v40, v40
	s_nop 0
	v_mul_f32_e32 v16, v40, v16
	v_mul_f32_e32 v16, v9, v16
	v_cvt_pk_bf16_f32 v16, v16, v17
	global_store_short v[42:43], v16, off
	v_lshl_add_u64 v[42:43], v[42:43], 0, s[86:87]
	s_waitcnt vmcnt(31)
	v_lshlrev_b32_e32 v16, 16, v182
	v_mul_f32_e32 v40, 0x3d372713, v16
	v_mul_f32_e32 v40, v40, v16
	v_fma_f32 v40, v40, v16, v16
	v_mul_f32_e32 v40, 0x3f4c422a, v40
	v_add_f32_e32 v40, v40, v40
	v_mul_f32_e32 v40, 0xbfb8aa3b, v40
	v_exp_f32_e32 v40, v40
	s_nop 0
	v_add_f32_e32 v40, 1.0, v40
	v_rcp_f32_e32 v40, v40
	s_nop 0
	v_mul_f32_e32 v16, v40, v16
	v_mul_f32_e32 v16, v10, v16
	v_cvt_pk_bf16_f32 v16, v16, v17
	global_store_short v[42:43], v16, off
	v_lshl_add_u64 v[42:43], v[42:43], 0, s[86:87]
	s_waitcnt vmcnt(31)
	v_lshlrev_b32_e32 v16, 16, v183
	v_mul_f32_e32 v40, 0x3d372713, v16
	v_mul_f32_e32 v40, v40, v16
	v_fma_f32 v40, v40, v16, v16
	v_mul_f32_e32 v40, 0x3f4c422a, v40
	v_add_f32_e32 v40, v40, v40
	v_mul_f32_e32 v40, 0xbfb8aa3b, v40
	v_exp_f32_e32 v40, v40
	s_nop 0
	v_add_f32_e32 v40, 1.0, v40
	v_rcp_f32_e32 v40, v40
	s_nop 0
	v_mul_f32_e32 v16, v40, v16
	v_mul_f32_e32 v16, v11, v16
	v_cvt_pk_bf16_f32 v16, v16, v17
	global_store_short v[42:43], v16, off
	v_lshl_add_u64 v[42:43], v[42:43], 0, s[88:89]
	s_waitcnt vmcnt(31)
	v_lshlrev_b32_e32 v16, 16, v184
	v_mul_f32_e32 v40, 0x3d372713, v16
	v_mul_f32_e32 v40, v40, v16
	v_fma_f32 v40, v40, v16, v16
	v_mul_f32_e32 v40, 0x3f4c422a, v40
	v_add_f32_e32 v40, v40, v40
	v_mul_f32_e32 v40, 0xbfb8aa3b, v40
	v_exp_f32_e32 v40, v40
	s_nop 0
	v_add_f32_e32 v40, 1.0, v40
	v_rcp_f32_e32 v40, v40
	s_nop 0
	v_mul_f32_e32 v16, v40, v16
	v_mul_f32_e32 v16, v4, v16
	v_cvt_pk_bf16_f32 v16, v16, v17
	global_store_short v[42:43], v16, off
	v_lshl_add_u64 v[42:43], v[42:43], 0, s[86:87]
	s_waitcnt vmcnt(31)
	v_lshlrev_b32_e32 v16, 16, v185
	v_mul_f32_e32 v40, 0x3d372713, v16
	v_mul_f32_e32 v40, v40, v16
	v_fma_f32 v40, v40, v16, v16
	v_mul_f32_e32 v40, 0x3f4c422a, v40
	v_add_f32_e32 v40, v40, v40
	v_mul_f32_e32 v40, 0xbfb8aa3b, v40
	v_exp_f32_e32 v40, v40
	s_nop 0
	v_add_f32_e32 v40, 1.0, v40
	v_rcp_f32_e32 v40, v40
	s_nop 0
	v_mul_f32_e32 v16, v40, v16
	v_mul_f32_e32 v16, v5, v16
	v_cvt_pk_bf16_f32 v16, v16, v17
	global_store_short v[42:43], v16, off
	v_lshl_add_u64 v[42:43], v[42:43], 0, s[86:87]
	s_waitcnt vmcnt(31)
	v_lshlrev_b32_e32 v16, 16, v186
	v_mul_f32_e32 v40, 0x3d372713, v16
	v_mul_f32_e32 v40, v40, v16
	v_fma_f32 v40, v40, v16, v16
	v_mul_f32_e32 v40, 0x3f4c422a, v40
	v_add_f32_e32 v40, v40, v40
	v_mul_f32_e32 v40, 0xbfb8aa3b, v40
	v_exp_f32_e32 v40, v40
	s_nop 0
	v_add_f32_e32 v40, 1.0, v40
	v_rcp_f32_e32 v40, v40
	s_nop 0
	v_mul_f32_e32 v16, v40, v16
	v_mul_f32_e32 v16, v6, v16
	v_cvt_pk_bf16_f32 v16, v16, v17
	global_store_short v[42:43], v16, off
	v_lshl_add_u64 v[42:43], v[42:43], 0, s[86:87]
	s_waitcnt vmcnt(31)
	v_lshlrev_b32_e32 v16, 16, v187
	v_mul_f32_e32 v40, 0x3d372713, v16
	v_mul_f32_e32 v40, v40, v16
	v_fma_f32 v40, v40, v16, v16
	v_mul_f32_e32 v40, 0x3f4c422a, v40
	v_add_f32_e32 v40, v40, v40
	v_mul_f32_e32 v40, 0xbfb8aa3b, v40
	v_exp_f32_e32 v40, v40
	s_nop 0
	v_add_f32_e32 v40, 1.0, v40
	v_rcp_f32_e32 v40, v40
	s_nop 0
	v_mul_f32_e32 v16, v40, v16
	v_mul_f32_e32 v16, v7, v16
	v_cvt_pk_bf16_f32 v16, v16, v17
	global_store_short v[42:43], v16, off
	v_lshl_add_u64 v[42:43], v[42:43], 0, s[88:89]
	s_waitcnt vmcnt(31)
	v_lshlrev_b32_e32 v16, 16, v188
	v_mul_f32_e32 v40, 0x3d372713, v16
	v_mul_f32_e32 v40, v40, v16
	v_fma_f32 v40, v40, v16, v16
	v_mul_f32_e32 v40, 0x3f4c422a, v40
	v_add_f32_e32 v40, v40, v40
	v_mul_f32_e32 v40, 0xbfb8aa3b, v40
	v_exp_f32_e32 v40, v40
	s_nop 0
	v_add_f32_e32 v40, 1.0, v40
	v_rcp_f32_e32 v40, v40
	s_nop 0
	v_mul_f32_e32 v16, v40, v16
	v_mul_f32_e32 v16, v0, v16
	v_cvt_pk_bf16_f32 v16, v16, v17
	global_store_short v[42:43], v16, off
	v_lshl_add_u64 v[42:43], v[42:43], 0, s[86:87]
	s_waitcnt vmcnt(31)
	v_lshlrev_b32_e32 v16, 16, v189
	v_mul_f32_e32 v40, 0x3d372713, v16
	v_mul_f32_e32 v40, v40, v16
	v_fma_f32 v40, v40, v16, v16
	v_mul_f32_e32 v40, 0x3f4c422a, v40
	v_add_f32_e32 v40, v40, v40
	v_mul_f32_e32 v40, 0xbfb8aa3b, v40
	v_exp_f32_e32 v40, v40
	s_nop 0
	v_add_f32_e32 v40, 1.0, v40
	v_rcp_f32_e32 v40, v40
	s_nop 0
	v_mul_f32_e32 v16, v40, v16
	v_mul_f32_e32 v16, v1, v16
	v_cvt_pk_bf16_f32 v16, v16, v17
	global_store_short v[42:43], v16, off
	v_lshl_add_u64 v[42:43], v[42:43], 0, s[86:87]
	s_waitcnt vmcnt(31)
	v_lshlrev_b32_e32 v16, 16, v190
	v_mul_f32_e32 v40, 0x3d372713, v16
	v_mul_f32_e32 v40, v40, v16
	v_fma_f32 v40, v40, v16, v16
	v_mul_f32_e32 v40, 0x3f4c422a, v40
	v_add_f32_e32 v40, v40, v40
	v_mul_f32_e32 v40, 0xbfb8aa3b, v40
	v_exp_f32_e32 v40, v40
	s_nop 0
	v_add_f32_e32 v40, 1.0, v40
	v_rcp_f32_e32 v40, v40
	s_nop 0
	v_mul_f32_e32 v16, v40, v16
	v_mul_f32_e32 v16, v2, v16
	v_cvt_pk_bf16_f32 v16, v16, v17
	global_store_short v[42:43], v16, off
	v_lshl_add_u64 v[42:43], v[42:43], 0, s[86:87]
	s_waitcnt vmcnt(31)
	v_lshlrev_b32_e32 v16, 16, v191
	v_mul_f32_e32 v40, 0x3d372713, v16
	v_mul_f32_e32 v40, v40, v16
	v_fma_f32 v40, v40, v16, v16
	v_mul_f32_e32 v40, 0x3f4c422a, v40
	v_add_f32_e32 v40, v40, v40
	v_mul_f32_e32 v40, 0xbfb8aa3b, v40
	v_exp_f32_e32 v40, v40
	s_nop 0
	v_add_f32_e32 v40, 1.0, v40
	v_rcp_f32_e32 v40, v40
	s_nop 0
	v_mul_f32_e32 v16, v40, v16
	v_mul_f32_e32 v16, v3, v16
	v_cvt_pk_bf16_f32 v16, v16, v17
	global_store_short v[42:43], v16, off
	s_barrier

.LBB0_579:
	s_and_b32 s26, s36, 3
	s_lshl_b32 s24, s26, 15
	v_mov_b32_e32 v7, v208
	s_add_u32 s40, s37, s24
	s_addc_u32 s41, s38, 0
	v_lshlrev_b32_e32 v0, 4, v7
	v_and_b32_e32 v16, 0xf0, v0
	v_lshl_add_u64 v[0:1], s[40:41], 0, v[16:17]
	s_mov_b64 s[40:41], 0x298000
	v_ashrrev_i32_e32 v8, 4, v7
	v_lshl_add_u64 v[4:5], v[0:1], 0, s[40:41]
	v_lshlrev_b32_e32 v0, 7, v8
	v_ashrrev_i32_e32 v1, 31, v0
	v_lshl_add_u64 v[0:1], v[0:1], 1, v[4:5]
	global_load_dwordx4 v[0:3], v[0:1], off
	v_add_u32_e32 v6, 0, v16
	v_mad_u64_u32 v[8:9], s[40:41], v8, s80, v[6:7]
	s_add_i32 s24, s29, s28
	v_mov_b32_e32 v41, v17
	v_cmp_lt_i32_e32 vcc, v214, v212
	v_mov_b32_e32 v43, v17
	s_lshl_b32 s27, s26, 7
	s_waitcnt vmcnt(0)
	ds_write_b128 v8, v[0:3]
	v_add_u32_e32 v0, 0x200, v7
	v_ashrrev_i32_e32 v8, 4, v0
	v_lshlrev_b32_e32 v0, 7, v8
	v_ashrrev_i32_e32 v1, 31, v0
	v_lshl_add_u64 v[0:1], v[0:1], 1, v[4:5]
	global_load_dwordx4 v[0:3], v[0:1], off
	v_mad_u64_u32 v[8:9], s[40:41], v8, s80, v[6:7]
	s_waitcnt vmcnt(0)
	ds_write_b128 v8, v[0:3]
	v_add_u32_e32 v0, 0x400, v7
	v_ashrrev_i32_e32 v8, 4, v0
	v_lshlrev_b32_e32 v0, 7, v8
	v_ashrrev_i32_e32 v1, 31, v0
	v_lshl_add_u64 v[0:1], v[0:1], 1, v[4:5]
	global_load_dwordx4 v[0:3], v[0:1], off
	v_mad_u64_u32 v[8:9], s[40:41], v8, s80, v[6:7]
	s_waitcnt vmcnt(0)
	ds_write_b128 v8, v[0:3]
	v_add_u32_e32 v0, 0x600, v7
	v_ashrrev_i32_e32 v7, 4, v0
	v_lshlrev_b32_e32 v0, 7, v7
	v_ashrrev_i32_e32 v1, 31, v0
	v_lshl_add_u64 v[0:1], v[0:1], 1, v[4:5]
	global_load_dwordx4 v[0:3], v[0:1], off
	v_mad_u64_u32 v[4:5], s[40:41], v7, s80, v[6:7]
	s_waitcnt vmcnt(0)
	ds_write_b128 v4, v[0:3]
	v_add_u32_e32 v0, s24, v72
	v_ashrrev_i32_e32 v1, 31, v0
	v_lshlrev_b64 v[0:1], 13, v[0:1]
	v_lshl_add_u64 v[18:19], s[22:23], 0, v[0:1]
	v_lshl_add_u64 v[20:21], v[18:19], 0, v[40:41]
	global_load_dwordx4 v[0:3], v[20:21], off offset:2096
	global_load_dwordx4 v[4:7], v[20:21], off offset:2080
	global_load_dwordx4 v[8:11], v[20:21], off offset:2064
	global_load_dwordx4 v[12:15], v[20:21], off offset:2048
	s_mov_b32 s24, 0x3b000000
	s_waitcnt vmcnt(2)
	v_lshlrev_b32_e32 v59, 16, v4
	s_waitcnt vmcnt(1)
	v_lshlrev_b32_e32 v47, 16, v8
	s_waitcnt vmcnt(0)
	v_and_b32_e32 v25, 0xffff0000, v13
	v_lshlrev_b32_e32 v13, 16, v13
	v_and_b32_e32 v23, 0xffff0000, v12
	v_lshlrev_b32_e32 v12, 16, v12
	v_mov_b32_e32 v16, v13
	v_pk_mul_f32 v[28:29], v[12:13], v[16:17] op_sel:[1,0] op_sel_hi:[0,1]
	v_pk_add_f32 v[30:31], v[12:13], v[22:23] op_sel:[1,0] op_sel_hi:[0,1]
	v_mul_f32_e32 v26, v12, v12
	v_mov_b32_e32 v29, v31
	v_mul_f32_e32 v16, v25, v25
	v_lshlrev_b32_e32 v31, 16, v14
	v_and_b32_e32 v33, 0xffff0000, v14
	v_mov_b32_e32 v27, v13
	v_mul_f32_e32 v24, v23, v23
	v_mul_f32_e32 v30, v31, v31
	v_mul_f32_e32 v32, v33, v33
	v_lshlrev_b32_e32 v45, 16, v15
	v_and_b32_e32 v15, 0xffff0000, v15
	v_pk_add_f32 v[12:13], v[26:27], v[24:25]
	v_pk_add_f32 v[22:23], v[28:29], v[16:17]
	v_mul_f32_e32 v44, v45, v45
	v_mul_f32_e32 v14, v15, v15
	v_and_b32_e32 v49, 0xffff0000, v8
	v_pk_add_f32 v[12:13], v[12:13], v[22:23]
	v_pk_add_f32 v[22:23], v[30:31], v[32:33]
	v_mul_f32_e32 v46, v47, v47
	v_mul_f32_e32 v48, v49, v49
	v_lshlrev_b32_e32 v51, 16, v9
	v_and_b32_e32 v9, 0xffff0000, v9
	v_pk_add_f32 v[12:13], v[22:23], v[12:13]
	v_pk_add_f32 v[14:15], v[44:45], v[14:15]
	v_mul_f32_e32 v50, v51, v51
	v_mul_f32_e32 v8, v9, v9
	v_lshlrev_b32_e32 v53, 16, v10
	v_and_b32_e32 v55, 0xffff0000, v10
	v_pk_add_f32 v[12:13], v[14:15], v[12:13]
	v_pk_add_f32 v[14:15], v[46:47], v[48:49]
	v_mul_f32_e32 v52, v53, v53
	v_mul_f32_e32 v54, v55, v55
	v_lshlrev_b32_e32 v57, 16, v11
	v_and_b32_e32 v11, 0xffff0000, v11
	v_pk_add_f32 v[12:13], v[14:15], v[12:13]
	v_pk_add_f32 v[8:9], v[50:51], v[8:9]
	v_mul_f32_e32 v56, v57, v57
	v_mul_f32_e32 v10, v11, v11
	v_and_b32_e32 v61, 0xffff0000, v4
	v_pk_add_f32 v[8:9], v[8:9], v[12:13]
	v_pk_add_f32 v[12:13], v[52:53], v[54:55]
	v_mul_f32_e32 v58, v59, v59
	v_mul_f32_e32 v60, v61, v61
	v_lshlrev_b32_e32 v63, 16, v5
	v_and_b32_e32 v5, 0xffff0000, v5
	v_pk_add_f32 v[8:9], v[12:13], v[8:9]
	v_pk_add_f32 v[10:11], v[56:57], v[10:11]
	v_mul_f32_e32 v62, v63, v63
	v_mul_f32_e32 v4, v5, v5
	v_lshlrev_b32_e32 v65, 16, v6
	v_and_b32_e32 v67, 0xffff0000, v6
	v_pk_add_f32 v[8:9], v[10:11], v[8:9]
	v_pk_add_f32 v[10:11], v[58:59], v[60:61]
	v_mul_f32_e32 v64, v65, v65
	v_mul_f32_e32 v66, v67, v67
	v_pk_add_f32 v[8:9], v[10:11], v[8:9]
	v_pk_add_f32 v[4:5], v[62:63], v[4:5]
	v_lshlrev_b32_e32 v27, 16, v0
	v_pk_add_f32 v[4:5], v[4:5], v[8:9]
	v_pk_add_f32 v[8:9], v[64:65], v[66:67]
	v_and_b32_e32 v29, 0xffff0000, v0
	v_pk_add_f32 v[22:23], v[8:9], v[4:5]
	v_lshlrev_b32_e32 v5, 16, v7
	v_and_b32_e32 v7, 0xffff0000, v7
	v_mul_f32_e32 v4, v5, v5
	v_mul_f32_e32 v6, v7, v7
	v_pk_add_f32 v[24:25], v[4:5], v[6:7]
	v_lshlrev_b32_e32 v31, 16, v1
	v_and_b32_e32 v33, 0xffff0000, v1
	v_lshlrev_b32_e32 v45, 16, v2
	v_and_b32_e32 v47, 0xffff0000, v2
	v_lshlrev_b32_e32 v49, 16, v3
	v_and_b32_e32 v51, 0xffff0000, v3
	global_load_dwordx4 v[0:3], v[20:21], off offset:2160
	global_load_dwordx4 v[4:7], v[20:21], off offset:2144
	global_load_dwordx4 v[8:11], v[20:21], off offset:2128
	global_load_dwordx4 v[12:15], v[20:21], off offset:2112
	v_mul_f32_e32 v26, v27, v27
	v_mul_f32_e32 v28, v29, v29
	v_mul_f32_e32 v30, v31, v31
	v_mul_f32_e32 v32, v33, v33
	v_pk_add_f32 v[22:23], v[24:25], v[22:23]
	v_pk_add_f32 v[24:25], v[26:27], v[28:29]
	v_mul_f32_e32 v44, v45, v45
	v_mul_f32_e32 v46, v47, v47
	v_pk_add_f32 v[22:23], v[24:25], v[22:23]
	v_pk_add_f32 v[24:25], v[30:31], v[32:33]
	v_mul_f32_e32 v48, v49, v49
	v_mul_f32_e32 v50, v51, v51
	v_pk_add_f32 v[22:23], v[24:25], v[22:23]
	v_pk_add_f32 v[24:25], v[44:45], v[46:47]
	v_cndmask_b32_e32 v16, v211, v214, vcc
	v_pk_add_f32 v[22:23], v[24:25], v[22:23]
	v_pk_add_f32 v[24:25], v[48:49], v[50:51]
	v_lshlrev_b32_e32 v16, 2, v16
	v_pk_add_f32 v[22:23], v[24:25], v[22:23]
	v_cmp_lt_i32_e32 vcc, v215, v212
	s_waitcnt vmcnt(3)
	v_lshlrev_b32_e32 v45, 16, v0
	s_waitcnt vmcnt(2)
	v_lshlrev_b32_e32 v49, 16, v7
	s_waitcnt vmcnt(1)
	v_lshlrev_b32_e32 v65, 16, v8
	s_waitcnt vmcnt(0)
	v_lshlrev_b32_e32 v53, 16, v12
	v_and_b32_e32 v55, 0xffff0000, v12
	v_mul_f32_e32 v52, v53, v53
	v_mul_f32_e32 v54, v55, v55
	v_lshlrev_b32_e32 v57, 16, v13
	v_and_b32_e32 v13, 0xffff0000, v13
	v_mul_f32_e32 v56, v57, v57
	v_mul_f32_e32 v12, v13, v13
	v_lshlrev_b32_e32 v59, 16, v14
	v_and_b32_e32 v61, 0xffff0000, v14
	v_pk_add_f32 v[24:25], v[52:53], v[54:55]
	v_mul_f32_e32 v58, v59, v59
	v_mul_f32_e32 v60, v61, v61
	v_lshlrev_b32_e32 v63, 16, v15
	v_and_b32_e32 v15, 0xffff0000, v15
	v_pk_add_f32 v[22:23], v[24:25], v[22:23]
	v_pk_add_f32 v[12:13], v[56:57], v[12:13]
	v_mul_f32_e32 v62, v63, v63
	v_mul_f32_e32 v14, v15, v15
	v_and_b32_e32 v67, 0xffff0000, v8
	v_pk_add_f32 v[12:13], v[12:13], v[22:23]
	v_pk_add_f32 v[22:23], v[58:59], v[60:61]
	v_mul_f32_e32 v64, v65, v65
	v_mul_f32_e32 v66, v67, v67
	v_lshlrev_b32_e32 v69, 16, v9
	v_and_b32_e32 v9, 0xffff0000, v9
	v_pk_add_f32 v[12:13], v[22:23], v[12:13]
	v_pk_add_f32 v[14:15], v[62:63], v[14:15]
	v_mul_f32_e32 v68, v69, v69
	v_mul_f32_e32 v8, v9, v9
	v_pk_add_f32 v[12:13], v[14:15], v[12:13]
	v_pk_add_f32 v[14:15], v[64:65], v[66:67]
	v_pk_add_f32 v[8:9], v[68:69], v[8:9]
	v_pk_add_f32 v[12:13], v[14:15], v[12:13]
	v_lshlrev_b32_e32 v67, 16, v11
	v_pk_add_f32 v[62:63], v[8:9], v[12:13]
	v_lshlrev_b32_e32 v9, 16, v10
	v_and_b32_e32 v13, 0xffff0000, v10
	v_mul_f32_e32 v8, v9, v9
	v_mul_f32_e32 v12, v13, v13
	v_pk_add_f32 v[70:71], v[8:9], v[12:13]
	v_and_b32_e32 v69, 0xffff0000, v11
	v_lshlrev_b32_e32 v61, 16, v4
	v_and_b32_e32 v65, 0xffff0000, v4
	v_lshlrev_b32_e32 v57, 16, v5
	v_and_b32_e32 v59, 0xffff0000, v5
	v_lshlrev_b32_e32 v53, 16, v6
	v_and_b32_e32 v55, 0xffff0000, v6
	v_and_b32_e32 v51, 0xffff0000, v7
	v_and_b32_e32 v47, 0xffff0000, v0
	v_lshlrev_b32_e32 v31, 16, v1
	v_and_b32_e32 v33, 0xffff0000, v1
	v_lshlrev_b32_e32 v27, 16, v2
	v_and_b32_e32 v29, 0xffff0000, v2
	v_lshlrev_b32_e32 v23, 16, v3
	v_and_b32_e32 v25, 0xffff0000, v3
	global_load_dwordx4 v[0:3], v[20:21], off offset:2224
	global_load_dwordx4 v[4:7], v[20:21], off offset:2208
	global_load_dwordx4 v[8:11], v[20:21], off offset:2192
	global_load_dwordx4 v[12:15], v[20:21], off offset:2176
	v_mul_f32_e32 v66, v67, v67
	v_mul_f32_e32 v68, v69, v69
	v_mul_f32_e32 v60, v61, v61
	v_mul_f32_e32 v64, v65, v65
	v_pk_add_f32 v[62:63], v[70:71], v[62:63]
	v_pk_add_f32 v[66:67], v[66:67], v[68:69]
	v_mul_f32_e32 v56, v57, v57
	v_mul_f32_e32 v58, v59, v59
	v_pk_add_f32 v[62:63], v[66:67], v[62:63]
	v_pk_add_f32 v[60:61], v[60:61], v[64:65]
	v_mul_f32_e32 v52, v53, v53
	v_mul_f32_e32 v54, v55, v55
	v_pk_add_f32 v[60:61], v[60:61], v[62:63]
	v_pk_add_f32 v[56:57], v[56:57], v[58:59]
	v_mul_f32_e32 v48, v49, v49
	v_mul_f32_e32 v50, v51, v51
	v_pk_add_f32 v[56:57], v[56:57], v[60:61]
	v_pk_add_f32 v[52:53], v[52:53], v[54:55]
	v_mul_f32_e32 v44, v45, v45
	v_mul_f32_e32 v46, v47, v47
	v_pk_add_f32 v[52:53], v[52:53], v[56:57]
	v_pk_add_f32 v[48:49], v[48:49], v[50:51]
	v_mul_f32_e32 v30, v31, v31
	v_mul_f32_e32 v32, v33, v33
	v_pk_add_f32 v[48:49], v[48:49], v[52:53]
	v_pk_add_f32 v[44:45], v[44:45], v[46:47]
	v_mul_f32_e32 v26, v27, v27
	v_mul_f32_e32 v28, v29, v29
	v_pk_add_f32 v[44:45], v[44:45], v[48:49]
	v_pk_add_f32 v[30:31], v[30:31], v[32:33]
	v_mul_f32_e32 v22, v23, v23
	v_mul_f32_e32 v24, v25, v25
	v_pk_add_f32 v[30:31], v[30:31], v[44:45]
	v_pk_add_f32 v[26:27], v[26:27], v[28:29]
	v_pk_add_f32 v[22:23], v[22:23], v[24:25]
	v_pk_add_f32 v[26:27], v[26:27], v[30:31]
	v_cndmask_b32_e32 v41, v211, v215, vcc
	v_pk_add_f32 v[22:23], v[22:23], v[26:27]
	v_lshlrev_b32_e32 v41, 2, v41
	s_waitcnt vmcnt(2)
	v_lshlrev_b32_e32 v53, 16, v4
	s_waitcnt vmcnt(1)
	v_lshlrev_b32_e32 v31, 16, v8
	s_waitcnt vmcnt(0)
	v_lshlrev_b32_e32 v81, 16, v12
	v_and_b32_e32 v83, 0xffff0000, v12
	v_mul_f32_e32 v80, v81, v81
	v_mul_f32_e32 v82, v83, v83
	v_pk_add_f32 v[24:25], v[80:81], v[82:83]
	v_and_b32_e32 v27, 0xffff0000, v14
	v_pk_add_f32 v[22:23], v[24:25], v[22:23]
	v_lshlrev_b32_e32 v25, 16, v13
	v_and_b32_e32 v13, 0xffff0000, v13
	v_mul_f32_e32 v24, v25, v25
	v_mul_f32_e32 v12, v13, v13
	v_pk_add_f32 v[12:13], v[24:25], v[12:13]
	v_lshlrev_b32_e32 v25, 16, v14
	v_mul_f32_e32 v24, v25, v25
	v_mul_f32_e32 v26, v27, v27
	v_lshlrev_b32_e32 v29, 16, v15
	v_and_b32_e32 v15, 0xffff0000, v15
	v_mul_f32_e32 v28, v29, v29
	v_mul_f32_e32 v14, v15, v15
	v_and_b32_e32 v33, 0xffff0000, v8
	v_pk_add_f32 v[12:13], v[12:13], v[22:23]
	v_pk_add_f32 v[22:23], v[24:25], v[26:27]
	v_mul_f32_e32 v30, v31, v31
	v_mul_f32_e32 v32, v33, v33
	v_lshlrev_b32_e32 v45, 16, v9
	v_and_b32_e32 v9, 0xffff0000, v9
	v_pk_add_f32 v[12:13], v[22:23], v[12:13]
	v_pk_add_f32 v[14:15], v[28:29], v[14:15]
	v_mul_f32_e32 v44, v45, v45
	v_mul_f32_e32 v8, v9, v9
	v_lshlrev_b32_e32 v47, 16, v10
	v_and_b32_e32 v49, 0xffff0000, v10
	v_pk_add_f32 v[12:13], v[14:15], v[12:13]
	v_pk_add_f32 v[14:15], v[30:31], v[32:33]
	v_mul_f32_e32 v46, v47, v47
	v_mul_f32_e32 v48, v49, v49
	v_lshlrev_b32_e32 v51, 16, v11
	v_and_b32_e32 v11, 0xffff0000, v11
	v_pk_add_f32 v[12:13], v[14:15], v[12:13]
	v_pk_add_f32 v[8:9], v[44:45], v[8:9]
	v_mul_f32_e32 v50, v51, v51
	v_mul_f32_e32 v10, v11, v11
	v_and_b32_e32 v55, 0xffff0000, v4
	v_pk_add_f32 v[8:9], v[8:9], v[12:13]
	v_pk_add_f32 v[12:13], v[46:47], v[48:49]
	v_mul_f32_e32 v52, v53, v53
	v_mul_f32_e32 v54, v55, v55
	v_lshlrev_b32_e32 v57, 16, v5
	v_and_b32_e32 v5, 0xffff0000, v5
	v_pk_add_f32 v[8:9], v[12:13], v[8:9]
	v_pk_add_f32 v[10:11], v[50:51], v[10:11]
	v_mul_f32_e32 v56, v57, v57
	v_mul_f32_e32 v4, v5, v5
	v_lshlrev_b32_e32 v59, 16, v6
	v_and_b32_e32 v61, 0xffff0000, v6
	v_pk_add_f32 v[8:9], v[10:11], v[8:9]
	v_pk_add_f32 v[10:11], v[52:53], v[54:55]
	v_mul_f32_e32 v58, v59, v59
	v_mul_f32_e32 v60, v61, v61
	v_lshlrev_b32_e32 v63, 16, v7
	v_and_b32_e32 v7, 0xffff0000, v7
	v_pk_add_f32 v[8:9], v[10:11], v[8:9]
	v_pk_add_f32 v[4:5], v[56:57], v[4:5]
	v_mul_f32_e32 v62, v63, v63
	v_mul_f32_e32 v6, v7, v7
	v_pk_add_f32 v[4:5], v[4:5], v[8:9]
	v_pk_add_f32 v[8:9], v[58:59], v[60:61]
	v_pk_add_f32 v[6:7], v[62:63], v[6:7]
	v_pk_add_f32 v[4:5], v[8:9], v[4:5]
	v_lshlrev_b32_e32 v33, 16, v1
	v_pk_add_f32 v[28:29], v[6:7], v[4:5]
	v_lshlrev_b32_e32 v5, 16, v0
	v_and_b32_e32 v7, 0xffff0000, v0
	v_mul_f32_e32 v4, v5, v5
	v_mul_f32_e32 v6, v7, v7
	v_pk_add_f32 v[46:47], v[4:5], v[6:7]
	v_and_b32_e32 v45, 0xffff0000, v1
	v_lshlrev_b32_e32 v27, 16, v2
	v_and_b32_e32 v31, 0xffff0000, v2
	v_lshlrev_b32_e32 v23, 16, v3
	v_and_b32_e32 v25, 0xffff0000, v3
	global_load_dwordx4 v[0:3], v[20:21], off offset:2288
	global_load_dwordx4 v[4:7], v[20:21], off offset:2272
	global_load_dwordx4 v[8:11], v[20:21], off offset:2256
	global_load_dwordx4 v[12:15], v[20:21], off offset:2240
	v_mul_f32_e32 v32, v33, v33
	v_mul_f32_e32 v44, v45, v45
	v_mul_f32_e32 v26, v27, v27
	v_mul_f32_e32 v30, v31, v31
	v_pk_add_f32 v[28:29], v[46:47], v[28:29]
	v_pk_add_f32 v[32:33], v[32:33], v[44:45]
	v_mul_f32_e32 v22, v23, v23
	v_mul_f32_e32 v24, v25, v25
	v_pk_add_f32 v[28:29], v[32:33], v[28:29]
	v_pk_add_f32 v[26:27], v[26:27], v[30:31]
	v_pk_add_f32 v[22:23], v[22:23], v[24:25]
	v_pk_add_f32 v[26:27], v[26:27], v[28:29]
	s_waitcnt vmcnt(3)
	v_lshlrev_b32_e32 v29, 16, v0
	v_pk_add_f32 v[22:23], v[22:23], v[26:27]
	s_waitcnt vmcnt(1)
	v_lshlrev_b32_e32 v59, 16, v8
	s_waitcnt vmcnt(0)
	v_lshlrev_b32_e32 v21, 16, v12
	v_and_b32_e32 v49, 0xffff0000, v12
	v_mul_f32_e32 v20, v21, v21
	v_mul_f32_e32 v48, v49, v49
	v_lshlrev_b32_e32 v51, 16, v13
	v_and_b32_e32 v13, 0xffff0000, v13
	v_mul_f32_e32 v50, v51, v51
	v_mul_f32_e32 v12, v13, v13
	v_lshlrev_b32_e32 v53, 16, v14
	v_and_b32_e32 v55, 0xffff0000, v14
	v_pk_add_f32 v[20:21], v[20:21], v[48:49]
	v_mul_f32_e32 v52, v53, v53
	v_mul_f32_e32 v54, v55, v55
	v_lshlrev_b32_e32 v57, 16, v15
	v_and_b32_e32 v15, 0xffff0000, v15
	v_pk_add_f32 v[20:21], v[20:21], v[22:23]
	v_pk_add_f32 v[12:13], v[50:51], v[12:13]
	v_mul_f32_e32 v56, v57, v57
	v_mul_f32_e32 v14, v15, v15
	v_and_b32_e32 v61, 0xffff0000, v8
	v_pk_add_f32 v[12:13], v[12:13], v[20:21]
	v_pk_add_f32 v[20:21], v[52:53], v[54:55]
	v_mul_f32_e32 v58, v59, v59
	v_mul_f32_e32 v60, v61, v61
	v_lshlrev_b32_e32 v63, 16, v9
	v_and_b32_e32 v9, 0xffff0000, v9
	v_pk_add_f32 v[12:13], v[20:21], v[12:13]
	v_pk_add_f32 v[14:15], v[56:57], v[14:15]
	v_mul_f32_e32 v62, v63, v63
	v_mul_f32_e32 v8, v9, v9
	v_lshlrev_b32_e32 v65, 16, v10
	v_and_b32_e32 v67, 0xffff0000, v10
	v_pk_add_f32 v[12:13], v[14:15], v[12:13]
	v_pk_add_f32 v[14:15], v[58:59], v[60:61]
	v_mul_f32_e32 v64, v65, v65
	v_mul_f32_e32 v66, v67, v67
	v_pk_add_f32 v[12:13], v[14:15], v[12:13]
	v_pk_add_f32 v[8:9], v[62:63], v[8:9]
	v_and_b32_e32 v15, 0xffff0000, v4
	v_pk_add_f32 v[8:9], v[8:9], v[12:13]
	v_pk_add_f32 v[12:13], v[64:65], v[66:67]
	v_mul_f32_e32 v14, v15, v15
	v_pk_add_f32 v[8:9], v[12:13], v[8:9]
	v_lshlrev_b32_e32 v13, 16, v11
	v_and_b32_e32 v11, 0xffff0000, v11
	v_mul_f32_e32 v12, v13, v13
	v_mul_f32_e32 v10, v11, v11
	v_pk_add_f32 v[10:11], v[12:13], v[10:11]
	v_lshlrev_b32_e32 v13, 16, v4
	v_mul_f32_e32 v12, v13, v13
	v_lshlrev_b32_e32 v21, 16, v5
	v_and_b32_e32 v5, 0xffff0000, v5
	v_mul_f32_e32 v20, v21, v21
	v_mul_f32_e32 v4, v5, v5
	v_lshlrev_b32_e32 v23, 16, v6
	v_and_b32_e32 v25, 0xffff0000, v6
	v_pk_add_f32 v[8:9], v[10:11], v[8:9]
	v_pk_add_f32 v[10:11], v[12:13], v[14:15]
	v_mul_f32_e32 v22, v23, v23
	v_mul_f32_e32 v24, v25, v25
	v_lshlrev_b32_e32 v27, 16, v7
	v_and_b32_e32 v7, 0xffff0000, v7
	v_pk_add_f32 v[8:9], v[10:11], v[8:9]
	v_pk_add_f32 v[4:5], v[20:21], v[4:5]
	v_mul_f32_e32 v26, v27, v27
	v_mul_f32_e32 v6, v7, v7
	v_and_b32_e32 v31, 0xffff0000, v0
	v_pk_add_f32 v[4:5], v[4:5], v[8:9]
	v_pk_add_f32 v[8:9], v[22:23], v[24:25]
	v_mul_f32_e32 v28, v29, v29
	v_mul_f32_e32 v30, v31, v31
	v_lshlrev_b32_e32 v33, 16, v1
	v_and_b32_e32 v1, 0xffff0000, v1
	v_pk_add_f32 v[4:5], v[8:9], v[4:5]
	v_pk_add_f32 v[6:7], v[26:27], v[6:7]
	v_mul_f32_e32 v32, v33, v33
	v_mul_f32_e32 v0, v1, v1
	v_lshlrev_b32_e32 v45, 16, v2
	v_and_b32_e32 v47, 0xffff0000, v2
	v_pk_add_f32 v[4:5], v[6:7], v[4:5]
	v_pk_add_f32 v[6:7], v[28:29], v[30:31]
	v_mul_f32_e32 v44, v45, v45
	v_mul_f32_e32 v46, v47, v47
	v_lshlrev_b32_e32 v49, 16, v3
	v_and_b32_e32 v3, 0xffff0000, v3
	v_pk_add_f32 v[4:5], v[6:7], v[4:5]
	v_pk_add_f32 v[0:1], v[32:33], v[0:1]
	v_mul_f32_e32 v48, v49, v49
	v_mul_f32_e32 v2, v3, v3
	v_pk_add_f32 v[0:1], v[0:1], v[4:5]
	v_pk_add_f32 v[4:5], v[44:45], v[46:47]
	v_pk_add_f32 v[2:3], v[48:49], v[2:3]
	v_pk_add_f32 v[0:1], v[4:5], v[0:1]
	s_nop 0
	v_pk_add_f32 v[0:1], v[2:3], v[0:1]
	ds_bpermute_b32 v3, v16, v1
	ds_bpermute_b32 v2, v16, v0
	v_or_b32_e32 v16, s27, v73
	v_lshlrev_b32_e32 v16, 1, v16
	s_waitcnt lgkmcnt(0)
	v_pk_add_f32 v[0:1], v[0:1], v[2:3]
	ds_bpermute_b32 v3, v41, v1
	ds_bpermute_b32 v2, v41, v0
	s_waitcnt lgkmcnt(0)
	v_pk_add_f32 v[0:1], v[0:1], v[2:3]
	s_nop 0
	v_pk_mul_f32 v[4:5], v[0:1], s[24:25] op_sel_hi:[1,0]
	s_lshl_b32 s24, s26, 8
	v_fma_f32 v0, -v5, v5, v4
	v_max_f32_e32 v0, 0, v0
	v_add_f32_e32 v0, 0x358637bd, v0
	v_cmp_gt_f32_e32 vcc, s55, v0
	v_mul_f32_e32 v1, 0x4b800000, v0
	s_nop 0
	v_cndmask_b32_e32 v0, v0, v1, vcc
	v_rsq_f32_e32 v0, v0
	s_nop 0
	v_mul_f32_e32 v1, 0x45800000, v0
	v_cndmask_b32_e32 v4, v0, v1, vcc
	v_lshl_add_u64 v[0:1], v[18:19], 0, s[24:25]
	v_lshl_add_u64 v[8:9], v[0:1], 0, v[42:43]
	s_lshl_b32 s24, s26, 9
	v_lshl_add_u64 v[6:7], v[38:39], 0, s[24:25]
	global_load_dwordx4 v[192:195], v[8:9], off offset:2048
	global_load_dwordx4 v[196:199], v[8:9], off offset:2064
	global_load_dwordx4 v[200:203], v[8:9], off offset:2080
	global_load_dwordx4 v[204:207], v[8:9], off offset:2096
	global_load_dwordx4 v[160:163], v[6:7], off
	global_load_dwordx4 v[164:167], v[6:7], off offset:16
	global_load_dwordx4 v[168:171], v[6:7], off offset:32
	global_load_dwordx4 v[172:175], v[6:7], off offset:48
	global_load_dwordx4 v[176:179], v[6:7], off offset:64
	global_load_dwordx4 v[180:183], v[6:7], off offset:80
	global_load_dwordx4 v[184:187], v[6:7], off offset:96
	global_load_dwordx4 v[188:191], v[6:7], off offset:112
	s_waitcnt vmcnt(0)
	s_ashr_i32 s24, s28, 31
	s_ashr_i32 s26, s29, 31
	s_add_u32 s28, s29, s28
	s_addc_u32 s29, s26, s24
	s_waitcnt vmcnt(1)
	v_lshlrev_b32_e32 v10, 16, v192
	v_sub_f32_e32 v10, v10, v5
	v_mul_f32_e32 v10, v10, v4
	s_waitcnt vmcnt(0)
	v_mul_f32_e32 v10, v160, v10
	v_cvt_pk_bf16_f32 v10, v10, v17
	ds_write_b16 v74, v10 offset:34816
	v_and_b32_e32 v0, 0xffff0000, v192
	v_sub_f32_e32 v0, v0, v5
	v_mul_f32_e32 v0, v0, v4
	s_waitcnt vmcnt(0)
	v_mul_f32_e32 v0, v161, v0
	v_cvt_pk_bf16_f32 v0, v0, v17
	ds_write_b16 v74, v0 offset:35088
	v_lshlrev_b32_e32 v0, 16, v193
	v_sub_f32_e32 v0, v0, v5
	v_mul_f32_e32 v0, v0, v4
	s_waitcnt vmcnt(0)
	v_mul_f32_e32 v0, v162, v0
	v_cvt_pk_bf16_f32 v0, v0, v17
	ds_write_b16 v74, v0 offset:35360
	v_and_b32_e32 v0, 0xffff0000, v193
	v_sub_f32_e32 v0, v0, v5
	v_mul_f32_e32 v0, v0, v4
	s_waitcnt vmcnt(0)
	v_mul_f32_e32 v0, v163, v0
	v_cvt_pk_bf16_f32 v0, v0, v17
	ds_write_b16 v74, v0 offset:35632
	v_lshlrev_b32_e32 v0, 16, v194
	v_sub_f32_e32 v0, v0, v5
	v_mul_f32_e32 v0, v0, v4
	s_waitcnt vmcnt(0)
	v_mul_f32_e32 v0, v164, v0
	v_cvt_pk_bf16_f32 v0, v0, v17
	ds_write_b16 v74, v0 offset:35904
	v_and_b32_e32 v0, 0xffff0000, v194
	v_sub_f32_e32 v0, v0, v5
	v_mul_f32_e32 v0, v0, v4
	s_waitcnt vmcnt(0)
	v_mul_f32_e32 v0, v165, v0
	v_cvt_pk_bf16_f32 v0, v0, v17
	ds_write_b16 v74, v0 offset:36176
	v_lshlrev_b32_e32 v0, 16, v195
	v_sub_f32_e32 v0, v0, v5
	v_mul_f32_e32 v0, v0, v4
	s_waitcnt vmcnt(0)
	v_mul_f32_e32 v0, v166, v0
	v_cvt_pk_bf16_f32 v0, v0, v17
	ds_write_b16 v74, v0 offset:36448
	v_and_b32_e32 v0, 0xffff0000, v195
	v_sub_f32_e32 v0, v0, v5
	v_mul_f32_e32 v0, v0, v4
	s_waitcnt vmcnt(0)
	v_mul_f32_e32 v0, v167, v0
	v_cvt_pk_bf16_f32 v0, v0, v17
	ds_write_b16 v74, v0 offset:36720
	s_waitcnt vmcnt(1)
	v_lshlrev_b32_e32 v10, 16, v196
	v_sub_f32_e32 v10, v10, v5
	v_mul_f32_e32 v10, v10, v4
	s_waitcnt vmcnt(0)
	v_mul_f32_e32 v10, v168, v10
	v_cvt_pk_bf16_f32 v10, v10, v17
	ds_write_b16 v75, v10 offset:34816
	v_and_b32_e32 v0, 0xffff0000, v196
	v_sub_f32_e32 v0, v0, v5
	v_mul_f32_e32 v0, v0, v4
	s_waitcnt vmcnt(0)
	v_mul_f32_e32 v0, v169, v0
	v_cvt_pk_bf16_f32 v0, v0, v17
	ds_write_b16 v75, v0 offset:35088
	v_lshlrev_b32_e32 v0, 16, v197
	v_sub_f32_e32 v0, v0, v5
	v_mul_f32_e32 v0, v0, v4
	s_waitcnt vmcnt(0)
	v_mul_f32_e32 v0, v170, v0
	v_cvt_pk_bf16_f32 v0, v0, v17
	ds_write_b16 v74, v0 offset:37536
	v_and_b32_e32 v0, 0xffff0000, v197
	v_sub_f32_e32 v0, v0, v5
	v_mul_f32_e32 v0, v0, v4
	s_waitcnt vmcnt(0)
	v_mul_f32_e32 v0, v171, v0
	v_cvt_pk_bf16_f32 v0, v0, v17
	ds_write_b16 v74, v0 offset:37808
	v_lshlrev_b32_e32 v0, 16, v198
	v_sub_f32_e32 v0, v0, v5
	v_mul_f32_e32 v0, v0, v4
	s_waitcnt vmcnt(0)
	v_mul_f32_e32 v0, v172, v0
	v_cvt_pk_bf16_f32 v0, v0, v17
	ds_write_b16 v74, v0 offset:38080
	v_and_b32_e32 v0, 0xffff0000, v198
	v_sub_f32_e32 v0, v0, v5
	v_mul_f32_e32 v0, v0, v4
	s_waitcnt vmcnt(0)
	v_mul_f32_e32 v0, v173, v0
	v_cvt_pk_bf16_f32 v0, v0, v17
	ds_write_b16 v74, v0 offset:38352
	v_lshlrev_b32_e32 v0, 16, v199
	v_sub_f32_e32 v0, v0, v5
	v_mul_f32_e32 v0, v0, v4
	s_waitcnt vmcnt(0)
	v_mul_f32_e32 v0, v174, v0
	v_cvt_pk_bf16_f32 v0, v0, v17
	ds_write_b16 v74, v0 offset:38624
	v_and_b32_e32 v0, 0xffff0000, v199
	v_sub_f32_e32 v0, v0, v5
	v_mul_f32_e32 v0, v0, v4
	s_waitcnt vmcnt(0)
	v_mul_f32_e32 v0, v175, v0
	v_cvt_pk_bf16_f32 v0, v0, v17
	ds_write_b16 v74, v0 offset:38896
	s_waitcnt vmcnt(1)
	v_lshlrev_b32_e32 v10, 16, v200
	v_sub_f32_e32 v10, v10, v5
	v_mul_f32_e32 v10, v10, v4
	s_waitcnt vmcnt(0)
	v_mul_f32_e32 v10, v176, v10
	v_cvt_pk_bf16_f32 v10, v10, v17
	ds_write_b16 v76, v10 offset:34816
	v_and_b32_e32 v0, 0xffff0000, v200
	v_sub_f32_e32 v0, v0, v5
	v_mul_f32_e32 v0, v0, v4
	s_waitcnt vmcnt(0)
	v_mul_f32_e32 v0, v177, v0
	v_cvt_pk_bf16_f32 v0, v0, v17
	ds_write_b16 v76, v0 offset:35088
	v_lshlrev_b32_e32 v0, 16, v201
	v_sub_f32_e32 v0, v0, v5
	v_mul_f32_e32 v0, v0, v4
	s_waitcnt vmcnt(0)
	v_mul_f32_e32 v0, v178, v0
	v_cvt_pk_bf16_f32 v0, v0, v17
	ds_write_b16 v74, v0 offset:39712
	v_and_b32_e32 v0, 0xffff0000, v201
	v_sub_f32_e32 v0, v0, v5
	v_mul_f32_e32 v0, v0, v4
	s_waitcnt vmcnt(0)
	v_mul_f32_e32 v0, v0, v179
	v_cvt_pk_bf16_f32 v0, v0, v17
	ds_write_b16 v74, v0 offset:39984
	v_lshlrev_b32_e32 v0, 16, v202
	v_sub_f32_e32 v0, v0, v5
	v_mul_f32_e32 v0, v0, v4
	s_waitcnt vmcnt(0)
	v_mul_f32_e32 v0, v0, v180
	v_cvt_pk_bf16_f32 v0, v0, v17
	ds_write_b16 v74, v0 offset:40256
	v_and_b32_e32 v0, 0xffff0000, v202
	v_sub_f32_e32 v0, v0, v5
	v_mul_f32_e32 v0, v0, v4
	s_waitcnt vmcnt(0)
	v_mul_f32_e32 v0, v0, v181
	v_cvt_pk_bf16_f32 v0, v0, v17
	ds_write_b16 v74, v0 offset:40528
	v_lshlrev_b32_e32 v0, 16, v203
	v_sub_f32_e32 v0, v0, v5
	v_mul_f32_e32 v0, v0, v4
	s_waitcnt vmcnt(0)
	v_mul_f32_e32 v0, v0, v182
	v_cvt_pk_bf16_f32 v0, v0, v17
	ds_write_b16 v74, v0 offset:40800
	v_and_b32_e32 v0, 0xffff0000, v203
	v_sub_f32_e32 v0, v0, v5
	v_mul_f32_e32 v0, v0, v4
	s_waitcnt vmcnt(0)
	v_mul_f32_e32 v0, v0, v183
	v_cvt_pk_bf16_f32 v0, v0, v17
	ds_write_b16 v74, v0 offset:41072
	s_waitcnt vmcnt(0)
	v_lshlrev_b32_e32 v8, 16, v204
	v_sub_f32_e32 v8, v8, v5
	v_mul_f32_e32 v8, v4, v8
	v_and_b32_e32 v0, 0xffff0000, v204
	v_sub_f32_e32 v0, v0, v5
	v_mul_f32_e32 v0, v4, v0
	s_waitcnt vmcnt(0)
	v_mul_f32_e32 v8, v184, v8
	v_cvt_pk_bf16_f32 v8, v8, v17
	ds_write_b16 v77, v8 offset:34816
	s_waitcnt vmcnt(0)
	v_mul_f32_e32 v0, v185, v0
	v_cvt_pk_bf16_f32 v0, v0, v17
	ds_write_b16 v77, v0 offset:35088
	v_lshlrev_b32_e32 v0, 16, v205
	v_sub_f32_e32 v0, v0, v5
	v_mul_f32_e32 v0, v4, v0
	s_waitcnt vmcnt(0)
	v_mul_f32_e32 v0, v0, v186
	v_cvt_pk_bf16_f32 v0, v0, v17
	ds_write_b16 v74, v0 offset:41888
	v_and_b32_e32 v0, 0xffff0000, v205
	v_sub_f32_e32 v0, v0, v5
	v_mul_f32_e32 v0, v4, v0
	s_waitcnt vmcnt(0)
	v_mul_f32_e32 v0, v0, v187
	v_cvt_pk_bf16_f32 v0, v0, v17
	ds_write_b16 v74, v0 offset:42160
	v_lshlrev_b32_e32 v0, 16, v206
	v_sub_f32_e32 v0, v0, v5
	v_mul_f32_e32 v0, v4, v0
	s_waitcnt vmcnt(0)
	v_mul_f32_e32 v0, v0, v188
	v_cvt_pk_bf16_f32 v0, v0, v17
	ds_write_b16 v74, v0 offset:42432
	v_and_b32_e32 v0, 0xffff0000, v206
	v_sub_f32_e32 v0, v0, v5
	v_mul_f32_e32 v0, v4, v0
	s_waitcnt vmcnt(0)
	v_mul_f32_e32 v0, v0, v189
	v_cvt_pk_bf16_f32 v0, v0, v17
	ds_write_b16 v74, v0 offset:42704
	v_lshlrev_b32_e32 v0, 16, v207
	v_sub_f32_e32 v0, v0, v5
	v_mul_f32_e32 v0, v4, v0
	s_waitcnt vmcnt(0)
	v_mul_f32_e32 v0, v0, v190
	v_cvt_pk_bf16_f32 v0, v0, v17
	ds_write_b16 v74, v0 offset:42976
	v_and_b32_e32 v0, 0xffff0000, v207
	v_sub_f32_e32 v0, v0, v5
	v_mul_f32_e32 v0, v4, v0
	s_waitcnt vmcnt(0)
	v_mul_f32_e32 v0, v0, v191
	v_cvt_pk_bf16_f32 v0, v0, v17
	ds_write_b16 v74, v0 offset:43248
	s_waitcnt lgkmcnt(0)
	s_barrier
	ds_read_b128 v[0:3], v36
	ds_read_b128 v[4:7], v78 offset:34816
	ds_read_b128 v[8:11], v78 offset:39168
	ds_read_b128 v[12:15], v78 offset:43520
	ds_read_b128 v[18:21], v78 offset:47872
	ds_read_b128 v[22:25], v78 offset:52224
	ds_read_b128 v[26:29], v78 offset:56576
	ds_read_b128 v[30:33], v78 offset:60928
	ds_read_b128 v[44:47], v78 offset:65280
	s_waitcnt lgkmcnt(7)
	v_mfma_f32_16x16x32_bf16 v[4:7], v[4:7], v[0:3], 0
	s_waitcnt lgkmcnt(6)
	v_mfma_f32_16x16x32_bf16 v[8:11], v[8:11], v[0:3], 0
	s_waitcnt lgkmcnt(5)
	v_mfma_f32_16x16x32_bf16 v[12:15], v[12:15], v[0:3], 0
	s_waitcnt lgkmcnt(4)
	v_mfma_f32_16x16x32_bf16 v[18:21], v[18:21], v[0:3], 0
	s_waitcnt lgkmcnt(3)
	v_mfma_f32_16x16x32_bf16 v[22:25], v[22:25], v[0:3], 0
	s_waitcnt lgkmcnt(2)
	v_mfma_f32_16x16x32_bf16 v[26:29], v[26:29], v[0:3], 0
	s_waitcnt lgkmcnt(1)
	v_mfma_f32_16x16x32_bf16 v[30:33], v[30:33], v[0:3], 0
	s_waitcnt lgkmcnt(0)
	v_mfma_f32_16x16x32_bf16 v[0:3], v[44:47], v[0:3], 0
	ds_read_b128 v[44:47], v36 offset:64
	ds_read_b128 v[48:51], v78 offset:34880
	s_waitcnt lgkmcnt(0)
	v_mfma_f32_16x16x32_bf16 v[4:7], v[48:51], v[44:47], v[4:7]
	ds_read_b128 v[48:51], v78 offset:39232
	s_waitcnt lgkmcnt(0)
	v_mfma_f32_16x16x32_bf16 v[8:11], v[48:51], v[44:47], v[8:11]
	ds_read_b128 v[48:51], v78 offset:43584
	s_waitcnt lgkmcnt(0)
	v_mfma_f32_16x16x32_bf16 v[12:15], v[48:51], v[44:47], v[12:15]
	ds_read_b128 v[48:51], v78 offset:47936
	s_waitcnt lgkmcnt(0)
	v_mfma_f32_16x16x32_bf16 v[18:21], v[48:51], v[44:47], v[18:21]
	ds_read_b128 v[48:51], v78 offset:52288
	s_waitcnt lgkmcnt(0)
	v_mfma_f32_16x16x32_bf16 v[22:25], v[48:51], v[44:47], v[22:25]
	ds_read_b128 v[48:51], v78 offset:56640
	s_waitcnt lgkmcnt(0)
	v_mfma_f32_16x16x32_bf16 v[26:29], v[48:51], v[44:47], v[26:29]
	ds_read_b128 v[48:51], v78 offset:60992
	s_waitcnt lgkmcnt(0)
	v_mfma_f32_16x16x32_bf16 v[30:33], v[48:51], v[44:47], v[30:33]
	ds_read_b128 v[48:51], v78 offset:65344
	s_waitcnt lgkmcnt(0)
	v_mfma_f32_16x16x32_bf16 v[0:3], v[48:51], v[44:47], v[0:3]
	ds_read_b128 v[44:47], v36 offset:128
	ds_read_b128 v[48:51], v78 offset:34944
	s_waitcnt lgkmcnt(0)
	v_mfma_f32_16x16x32_bf16 v[4:7], v[48:51], v[44:47], v[4:7]
	ds_read_b128 v[48:51], v78 offset:39296
	s_waitcnt lgkmcnt(0)
	v_mfma_f32_16x16x32_bf16 v[8:11], v[48:51], v[44:47], v[8:11]
	ds_read_b128 v[48:51], v78 offset:43648
	s_waitcnt lgkmcnt(0)
	v_mfma_f32_16x16x32_bf16 v[12:15], v[48:51], v[44:47], v[12:15]
	ds_read_b128 v[48:51], v78 offset:48000
	s_waitcnt lgkmcnt(0)
	v_mfma_f32_16x16x32_bf16 v[18:21], v[48:51], v[44:47], v[18:21]
	ds_read_b128 v[48:51], v78 offset:52352
	s_waitcnt lgkmcnt(0)
	v_mfma_f32_16x16x32_bf16 v[48:51], v[48:51], v[44:47], v[22:25]
	s_nop 2
	ds_read_b128 v[22:25], v78 offset:56704
	s_waitcnt lgkmcnt(0)
	v_mfma_f32_16x16x32_bf16 v[52:55], v[22:25], v[44:47], v[26:29]
	ds_read_b128 v[22:25], v78 offset:61056
	s_waitcnt lgkmcnt(0)
	v_mfma_f32_16x16x32_bf16 v[56:59], v[22:25], v[44:47], v[30:33]
	ds_read_b128 v[22:25], v78 offset:65408
	s_waitcnt lgkmcnt(0)
	v_mfma_f32_16x16x32_bf16 v[0:3], v[22:25], v[44:47], v[0:3]
	ds_read_b128 v[44:47], v36 offset:192
	ds_read_b128 v[22:25], v78 offset:35008
	s_waitcnt lgkmcnt(0)
	v_mfma_f32_16x16x32_bf16 v[30:33], v[22:25], v[44:47], v[4:7]
	s_nop 2
	ds_read_b128 v[4:7], v78 offset:39360
	s_waitcnt lgkmcnt(0)
	v_mfma_f32_16x16x32_bf16 v[26:29], v[4:7], v[44:47], v[8:11]
	ds_read_b128 v[4:7], v78 offset:43712
	s_waitcnt lgkmcnt(0)
	v_mfma_f32_16x16x32_bf16 v[22:25], v[4:7], v[44:47], v[12:15]
	ds_read_b128 v[4:7], v78 offset:48064
	s_waitcnt lgkmcnt(0)
	v_mfma_f32_16x16x32_bf16 v[18:21], v[4:7], v[44:47], v[18:21]
	ds_read_b128 v[4:7], v78 offset:52416
	s_waitcnt lgkmcnt(0)
	v_mfma_f32_16x16x32_bf16 v[12:15], v[4:7], v[44:47], v[48:51]
	ds_read_b128 v[4:7], v78 offset:56768
	s_nop 1
	ds_read_b128 v[48:51], v78 offset:65472
	s_waitcnt lgkmcnt(1)
	v_mfma_f32_16x16x32_bf16 v[8:11], v[4:7], v[44:47], v[52:55]
	ds_read_b128 v[4:7], v78 offset:61120
	s_waitcnt lgkmcnt(0)
	v_mfma_f32_16x16x32_bf16 v[4:7], v[4:7], v[44:47], v[56:59]
	v_mfma_f32_16x16x32_bf16 v[0:3], v[48:51], v[44:47], v[0:3]
	v_add_u32_e32 v44, s27, v37
	v_ashrrev_i32_e32 v45, 31, v44
	v_lshl_add_u64 v[44:45], v[44:45], 2, s[18:19]
	global_load_dword v41, v[44:45], off
	v_lshl_add_u64 v[44:45], s[28:29], 0, v[34:35]
	v_lshlrev_b64 v[46:47], 13, v[44:45]
	v_lshl_add_u64 v[46:47], s[22:23], 0, v[46:47]
	v_lshl_add_u64 v[46:47], v[46:47], 0, v[16:17]
	global_load_dwordx2 v[48:49], v[46:47], off offset:1024
	v_lshlrev_b64 v[44:45], 12, v[44:45]
	v_lshl_add_u64 v[44:45], s[0:1], 0, v[44:45]
	s_mov_b64 s[26:27], 0x23578400
	v_lshl_add_u64 v[44:45], v[44:45], 0, s[26:27]
	s_waitcnt vmcnt(1)
	v_add_f32_e32 v30, v30, v41
	v_add_f32_e32 v31, v31, v41
	v_add_f32_e32 v32, v32, v41
	v_add_f32_e32 v33, v33, v41
	v_add_f32_e32 v26, v26, v41
	s_waitcnt vmcnt(0)
	v_lshlrev_b32_e32 v43, 16, v48
	v_mul_f32_e32 v30, v30, v43
	v_and_b32_e32 v43, 0xffff0000, v48
	v_mul_f32_e32 v31, v31, v43
	v_cvt_pk_bf16_f32 v30, v30, v31
	v_lshlrev_b32_e32 v31, 16, v49
	v_mul_f32_e32 v31, v32, v31
	v_and_b32_e32 v32, 0xffff0000, v49
	v_mul_f32_e32 v32, v33, v32
	v_cvt_pk_bf16_f32 v31, v31, v32
	v_lshl_add_u64 v[32:33], v[44:45], 0, v[16:17]
	global_store_dwordx2 v[32:33], v[30:31], off
	global_load_dwordx2 v[30:31], v[46:47], off offset:1056
	v_add_f32_e32 v27, v27, v41
	v_add_f32_e32 v28, v28, v41
	v_add_f32_e32 v29, v29, v41
	v_add_f32_e32 v22, v22, v41
	v_add_f32_e32 v23, v23, v41
	v_add_f32_e32 v24, v24, v41
	v_add_f32_e32 v25, v25, v41
	v_add_f32_e32 v18, v18, v41
	v_add_f32_e32 v19, v19, v41
	v_add_f32_e32 v20, v20, v41
	v_add_f32_e32 v21, v21, v41
	v_add_f32_e32 v12, v12, v41
	v_add_f32_e32 v13, v13, v41
	v_add_f32_e32 v14, v14, v41
	v_add_f32_e32 v15, v15, v41
	v_add_f32_e32 v8, v8, v41
	v_add_f32_e32 v9, v9, v41
	v_add_f32_e32 v10, v10, v41
	v_add_f32_e32 v11, v11, v41
	v_add_f32_e32 v4, v4, v41
	v_add_f32_e32 v5, v5, v41
	v_add_f32_e32 v6, v6, v41
	v_add_f32_e32 v7, v7, v41
	v_add_f32_e32 v0, v41, v0
	v_add_f32_e32 v1, v41, v1
	v_add_f32_e32 v2, v41, v2
	v_add_f32_e32 v3, v41, v3
	s_waitcnt vmcnt(0)
	v_lshlrev_b32_e32 v32, 16, v30
	v_and_b32_e32 v30, 0xffff0000, v30
	v_mul_f32_e32 v26, v26, v32
	v_mul_f32_e32 v27, v27, v30
	v_cvt_pk_bf16_f32 v26, v26, v27
	v_lshlrev_b32_e32 v27, 16, v31
	v_mul_f32_e32 v27, v28, v27
	v_and_b32_e32 v28, 0xffff0000, v31
	v_mul_f32_e32 v28, v29, v28
	v_cvt_pk_bf16_f32 v27, v27, v28
	v_or_b32_e32 v28, 32, v16
	v_mov_b32_e32 v29, v17
	v_lshl_add_u64 v[28:29], v[44:45], 0, v[28:29]
	global_store_dwordx2 v[28:29], v[26:27], off
	global_load_dwordx2 v[26:27], v[46:47], off offset:1088
	s_waitcnt vmcnt(0)
	v_lshlrev_b32_e32 v28, 16, v26
	v_and_b32_e32 v26, 0xffff0000, v26
	v_mul_f32_e32 v22, v22, v28
	v_mul_f32_e32 v23, v23, v26
	v_cvt_pk_bf16_f32 v22, v22, v23
	v_lshlrev_b32_e32 v23, 16, v27
	v_mul_f32_e32 v23, v24, v23
	v_and_b32_e32 v24, 0xffff0000, v27
	v_mul_f32_e32 v24, v25, v24
	v_cvt_pk_bf16_f32 v23, v23, v24
	v_or_b32_e32 v24, 64, v16
	v_mov_b32_e32 v25, v17
	v_lshl_add_u64 v[24:25], v[44:45], 0, v[24:25]
	global_store_dwordx2 v[24:25], v[22:23], off
	global_load_dwordx2 v[22:23], v[46:47], off offset:1120
	s_waitcnt vmcnt(0)
	v_lshlrev_b32_e32 v24, 16, v22
	v_and_b32_e32 v22, 0xffff0000, v22
	v_mul_f32_e32 v18, v18, v24
	v_mul_f32_e32 v19, v19, v22
	v_cvt_pk_bf16_f32 v18, v18, v19
	v_lshlrev_b32_e32 v19, 16, v23
	v_mul_f32_e32 v19, v20, v19
	v_and_b32_e32 v20, 0xffff0000, v23
	v_mul_f32_e32 v20, v21, v20
	v_cvt_pk_bf16_f32 v19, v19, v20
	v_or_b32_e32 v20, 0x60, v16
	v_mov_b32_e32 v21, v17
	v_lshl_add_u64 v[20:21], v[44:45], 0, v[20:21]
	global_store_dwordx2 v[20:21], v[18:19], off
	global_load_dwordx2 v[18:19], v[46:47], off offset:1152
	s_waitcnt vmcnt(0)
	v_lshlrev_b32_e32 v20, 16, v18
	v_and_b32_e32 v18, 0xffff0000, v18
	v_mul_f32_e32 v12, v12, v20
	v_mul_f32_e32 v13, v13, v18
	v_cvt_pk_bf16_f32 v12, v12, v13
	v_lshlrev_b32_e32 v13, 16, v19
	v_mul_f32_e32 v13, v14, v13
	v_and_b32_e32 v14, 0xffff0000, v19
	v_mul_f32_e32 v14, v15, v14
	v_cvt_pk_bf16_f32 v13, v13, v14
	v_or_b32_e32 v14, 0x80, v16
	v_mov_b32_e32 v15, v17
	v_lshl_add_u64 v[14:15], v[44:45], 0, v[14:15]
	global_store_dwordx2 v[14:15], v[12:13], off
	global_load_dwordx2 v[12:13], v[46:47], off offset:1184
	s_waitcnt vmcnt(0)
	v_lshlrev_b32_e32 v14, 16, v12
	v_and_b32_e32 v12, 0xffff0000, v12
	v_mul_f32_e32 v8, v8, v14
	v_mul_f32_e32 v9, v9, v12
	v_cvt_pk_bf16_f32 v8, v8, v9
	v_lshlrev_b32_e32 v9, 16, v13
	v_mul_f32_e32 v9, v10, v9
	v_and_b32_e32 v10, 0xffff0000, v13
	v_mul_f32_e32 v10, v11, v10
	v_cvt_pk_bf16_f32 v9, v9, v10
	v_or_b32_e32 v10, 0xa0, v16
	v_mov_b32_e32 v11, v17
	v_lshl_add_u64 v[10:11], v[44:45], 0, v[10:11]
	global_store_dwordx2 v[10:11], v[8:9], off
	global_load_dwordx2 v[8:9], v[46:47], off offset:1216
	s_waitcnt vmcnt(0)
	v_lshlrev_b32_e32 v10, 16, v8
	v_and_b32_e32 v8, 0xffff0000, v8
	v_mul_f32_e32 v4, v4, v10
	v_mul_f32_e32 v5, v5, v8
	v_cvt_pk_bf16_f32 v4, v4, v5
	v_lshlrev_b32_e32 v5, 16, v9
	v_mul_f32_e32 v5, v6, v5
	v_and_b32_e32 v6, 0xffff0000, v9
	v_mul_f32_e32 v6, v7, v6
	v_cvt_pk_bf16_f32 v5, v5, v6
	v_or_b32_e32 v6, 0xc0, v16
	v_mov_b32_e32 v7, v17
	v_lshl_add_u64 v[6:7], v[44:45], 0, v[6:7]
	global_store_dwordx2 v[6:7], v[4:5], off
	global_load_dwordx2 v[4:5], v[46:47], off offset:1248
	v_or_b32_e32 v16, 0xe0, v16
	s_waitcnt vmcnt(0)
	v_lshlrev_b32_e32 v6, 16, v4
	v_and_b32_e32 v4, 0xffff0000, v4
	v_mul_f32_e32 v0, v0, v6
	v_mul_f32_e32 v1, v1, v4
	v_cvt_pk_bf16_f32 v0, v0, v1
	v_lshlrev_b32_e32 v1, 16, v5
	v_mul_f32_e32 v1, v2, v1
	v_and_b32_e32 v2, 0xffff0000, v5
	v_mul_f32_e32 v2, v3, v2
	v_cvt_pk_bf16_f32 v1, v1, v2
	v_lshl_add_u64 v[2:3], v[44:45], 0, v[16:17]
	global_store_dwordx2 v[2:3], v[0:1], off
	s_barrier
